# removed cg grid.sync at entry (xcd barrier census suffices)
# speedup vs baseline: 1.0071x; 1.0071x over previous
.LBB0_3:
	s_or_b64 exec, exec, s[4:5]
	s_cmp_eq_u32 s82, 0
	s_cselect_b64 s[4:5], -1, 0
	s_cmp_eq_u32 s83, 11
	s_cselect_b64 s[6:7], -1, 0
	s_and_b64 s[4:5], s[4:5], s[6:7]
	s_add_u32 s6, s78, 0x1e00000
	s_addc_u32 s7, s79, 0
	v_writelane_b32 v254, s6, 10
	s_mov_b32 s90, 0
	s_andn2_b64 vcc, exec, s[4:5]
	v_writelane_b32 v254, s7, 11
	s_waitcnt lgkmcnt(0)
	s_barrier
	s_cbranch_vccnz .LBB0_18
	v_lshrrev_b32_e32 v1, 20, v0
	v_lshrrev_b32_e32 v0, 10, v0
	v_or_b32_e32 v0, v0, v1
	s_movk_i32 s4, 0x3ff
	v_and_or_b32 v0, v0, s4, v210
	v_cmp_eq_u32_e32 vcc, 0, v0
	s_barrier
	s_and_saveexec_b64 s[4:5], vcc
.LBB0_14:
	s_or_b64 exec, exec, s[4:5]
	s_barrier
	s_getreg_b32 s4, hwreg(HW_REG_XCC_ID, 0, 4)
	s_and_b32 s90, s4, 15
	v_cmp_eq_u32_e32 vcc, 0, v210
	s_and_saveexec_b64 s[4:5], vcc
	s_cbranch_execz .LBB0_17
	s_mov_b64 s[6:7], exec
	v_mbcnt_lo_u32_b32 v0, s6, 0
	v_mbcnt_hi_u32_b32 v0, s7, v0
	v_cmp_eq_u32_e32 vcc, 0, v0
	s_and_b64 s[8:9], exec, vcc
	s_mov_b64 exec, s[8:9]
	s_cbranch_execz .LBB0_17
	s_bcnt1_i32_b64 s6, s[6:7]
	s_lshl_b32 s8, s90, 8
	v_mov_b32_e32 v1, s6
	v_readlane_b32 s6, v254, 10
	v_mov_b32_e32 v0, s8
	v_readlane_b32 s7, v254, 11
	s_nop 4
	global_atomic_add v0, v1, s[6:7] offset:1024
